# normmod2: shift/scale loads before the next-row prefetch, counted vmcnt(8), next-row wait at first use (same as normmod1)
# baseline (speedup 1.0000x reference)
; __device__ __forceinline__ void phase_normmod(const float* src, const float* gain, const float* ada, int shoff, int scoff, bf16_t* dst) {
;     ...
;     for (int m = gw; m < M_; m += NGW) {
;         const int mn = (m + NGW < M_) ? m + NGW : m;
;         const float* ab = ada + (size_t)(m >> 12) * NADA;
;         f32x4 vn[8], sh[8], sc[8];
; #pragma unroll
;         for (int j = 0; j < 8; ++j) { const int col = 4 * (lane + 64 * j); sh[j] = *(const f32x4*)(ab + shoff + col); sc[j] = *(const f32x4*)(ab + scoff + col); vn[j] = ((const f32x4*)(src + (size_t)mn * D_) + lane)[64 * j]; }
;         __builtin_amdgcn_sched_barrier(0);
;         float ss = 0.f;
; #pragma unroll
;         for (int j = 0; j < 8; ++j) ss += (v[j][0] * v[j][0] + v[j][1] * v[j][1]) + (v[j][2] * v[j][2] + v[j][3] * v[j][3]);
;         ss = wave_sum(ss);
;         const float rstd = rsqrtf(ss * (1.0f / D_) + 1e-6f);
.LBB0_335:
	v_add_u32_e32 v217, s64, v128
	v_cmp_gt_i32_e32 vcc, s2, v217
	v_ashrrev_i32_e32 v65, 12, v128
	v_mul_hi_i32_i24_e32 v67, 0x12000, v65
	v_cndmask_b32_e32 v64, v128, v217, vcc
	v_mul_i32_i24_e32 v66, 0x12000, v65
	v_lshl_add_u64 v[66:67], s[70:71], 0, v[66:67]
	v_ashrrev_i32_e32 v65, 31, v64
	v_lshl_add_u64 v[96:97], v[66:67], 0, s[12:13]
	v_lshl_add_u64 v[98:99], v[66:67], 0, s[14:15]
	v_lshlrev_b64 v[64:65], 13, v[64:65]
	v_lshl_add_u64 v[84:85], v[144:145], 0, v[64:65]
	v_lshl_add_u64 v[64:65], v[96:97], 0, v[142:143]
	v_lshl_add_u64 v[68:69], v[98:99], 0, v[142:143]
	v_mov_b32_e32 v149, v143
	global_load_dwordx4 v[64:67], v[64:65], off
	s_nop 0
	global_load_dwordx4 v[172:175], v[68:69], off
	v_lshl_add_u64 v[68:69], v[96:97], 0, v[148:149]
	v_lshl_add_u64 v[72:73], v[98:99], 0, v[148:149]
	v_mov_b32_e32 v151, v143
	global_load_dwordx4 v[68:71], v[68:69], off
	s_nop 0
	global_load_dwordx4 v[184:187], v[72:73], off
	v_lshl_add_u64 v[72:73], v[96:97], 0, v[150:151]
	v_lshl_add_u64 v[76:77], v[98:99], 0, v[150:151]
	v_mov_b32_e32 v153, v143
	global_load_dwordx4 v[72:75], v[72:73], off
	s_nop 0
	global_load_dwordx4 v[190:193], v[76:77], off
	v_lshl_add_u64 v[76:77], v[96:97], 0, v[152:153]
	v_lshl_add_u64 v[80:81], v[98:99], 0, v[152:153]
	v_mov_b32_e32 v155, v143
	v_add_co_u32_e32 v124, vcc, s6, v84
	v_mov_b32_e32 v157, v143
	global_load_dwordx4 v[76:79], v[76:77], off
	s_nop 0
	global_load_dwordx4 v[198:201], v[80:81], off
	v_lshl_add_u64 v[80:81], v[96:97], 0, v[154:155]
	v_lshl_add_u64 v[86:87], v[98:99], 0, v[154:155]
	v_addc_co_u32_e32 v125, vcc, 0, v85, vcc
	v_lshl_add_u64 v[84:85], v[96:97], 0, v[156:157]
	v_lshl_add_u64 v[88:89], v[98:99], 0, v[156:157]
	v_mov_b32_e32 v159, v143
	global_load_dwordx4 v[80:83], v[80:81], off
	s_nop 0
	global_load_dwordx4 v[212:215], v[86:87], off
	s_nop 0
	global_load_dwordx4 v[84:87], v[84:85], off
	s_nop 0
	global_load_dwordx4 v[136:139], v[88:89], off
	v_lshl_add_u64 v[88:89], v[96:97], 0, v[158:159]
	v_lshl_add_u64 v[120:121], v[98:99], 0, v[158:159]
	v_mov_b32_e32 v161, v143
	global_load_dwordx4 v[88:91], v[88:89], off
	s_nop 0
	global_load_dwordx4 v[132:135], v[120:121], off
	v_lshl_add_u64 v[96:97], v[96:97], 0, v[160:161]
	v_lshl_add_u64 v[120:121], v[98:99], 0, v[160:161]
	global_load_dwordx4 v[96:99], v[96:97], off
	s_nop 0
	global_load_dwordx4 v[128:131], v[120:121], off
	s_nop 0
	s_nop 0
	global_load_dwordx4 v[100:103], v[124:125], off offset:-4096
	global_load_dwordx4 v[92:95], v[124:125], off offset:-3072
	global_load_dwordx4 v[108:111], v[124:125], off offset:-2048
	global_load_dwordx4 v[104:107], v[124:125], off offset:-1024
	global_load_dwordx4 v[116:119], v[124:125], off
	global_load_dwordx4 v[112:115], v[124:125], off offset:1024
	global_load_dwordx4 v[120:123], v[124:125], off offset:2048
	global_load_dwordx4 v[124:127], v[124:125], off offset:3072
	v_cmp_lt_i32_e32 vcc, s7, v217
	v_pk_mul_f32 v[180:181], v[38:39], v[38:39]
	v_pk_mul_f32 v[178:179], v[42:43], v[42:43]
	v_pk_mul_f32 v[188:189], v[36:37], v[36:37]
	v_pk_mul_f32 v[182:183], v[40:41], v[40:41]
	s_waitcnt vmcnt(8)
	v_pk_mul_f32 v[176:177], v[46:47], v[46:47]
	v_pk_mul_f32 v[170:171], v[44:45], v[44:45]
	v_pk_add_f32 v[162:163], v[174:175], 1.0 op_sel_hi:[1,0]
	v_pk_add_f32 v[174:175], v[184:185], 1.0 op_sel_hi:[1,0]
	v_pk_add_f32 v[184:185], v[192:193], 1.0 op_sel_hi:[1,0]
	v_pk_add_f32 v[192:193], v[198:199], 1.0 op_sel_hi:[1,0]
	v_pk_add_f32 v[198:199], v[214:215], 1.0 op_sel_hi:[1,0]
	v_mov_b32_e32 v214, v188
	v_mov_b32_e32 v215, v182
	v_mov_b32_e32 v182, v189
	v_mov_b32_e32 v188, v180
	v_mov_b32_e32 v189, v178
	v_mov_b32_e32 v178, v181
	v_pk_mov_b32 v[180:181], v[170:171], v[176:177] op_sel:[1,0]
	v_mov_b32_e32 v171, v177
	v_pk_add_f32 v[182:183], v[214:215], v[182:183]
	v_pk_add_f32 v[178:179], v[188:189], v[178:179]
	v_mul_f32_e32 v194, v48, v48
	v_mul_f32_e32 v196, v50, v50
	v_pk_add_f32 v[170:171], v[180:181], v[170:171]
	v_pk_add_f32 v[178:179], v[182:183], v[178:179]
	v_pk_fma_f32 v[176:177], v[48:49], v[48:49], v[194:195] op_sel_hi:[1,1,0]
	v_pk_fma_f32 v[218:219], v[50:51], v[50:51], v[196:197] op_sel_hi:[1,1,0]
	v_pk_add_f32 v[170:171], v[170:171], v[170:171] op_sel_hi:[0,1]
	v_pk_add_f32 v[178:179], v[178:179], v[178:179] op_sel_hi:[0,1]
	v_pk_mul_f32 v[168:169], v[62:63], v[62:63]
	v_pk_mul_f32 v[166:167], v[60:61], v[60:61]
	v_mul_f32_e32 v176, v52, v52
	v_mul_f32_e32 v218, v53, v53
	v_mul_f32_e32 v170, v54, v54
	v_mul_f32_e32 v178, v55, v55
	v_pk_mov_b32 v[220:221], v[166:167], v[168:169] op_sel:[1,0]
	v_mov_b32_e32 v167, v169
	v_pk_add_f32 v[176:177], v[176:177], v[218:219]
	v_pk_add_f32 v[170:171], v[170:171], v[178:179]
	v_mul_f32_e32 v202, v56, v56
	v_mul_f32_e32 v216, v58, v58
	v_pk_add_f32 v[166:167], v[220:221], v[166:167]
	v_pk_add_f32 v[170:171], v[176:177], v[170:171]
	v_pk_add_f32 v[164:165], v[172:173], 1.0 op_sel_hi:[1,0]
	v_pk_add_f32 v[172:173], v[186:187], 1.0 op_sel_hi:[1,0]
	v_pk_add_f32 v[186:187], v[190:191], 1.0 op_sel_hi:[1,0]
	v_pk_add_f32 v[190:191], v[200:201], 1.0 op_sel_hi:[1,0]
	v_pk_add_f32 v[200:201], v[212:213], 1.0 op_sel_hi:[1,0]
	v_pk_add_f32 v[212:213], v[128:129], 1.0 op_sel_hi:[1,0]
	v_mov_b32_e32 v128, v217
	v_pk_fma_f32 v[168:169], v[56:57], v[56:57], v[202:203] op_sel_hi:[1,1,0]
	v_pk_fma_f32 v[216:217], v[58:59], v[58:59], v[216:217] op_sel_hi:[1,1,0]
	v_pk_add_f32 v[166:167], v[166:167], v[166:167] op_sel_hi:[0,1]
	v_pk_add_f32 v[170:171], v[170:171], v[170:171] op_sel_hi:[0,1]
	v_mul_f32_e32 v168, v210, v210
	v_mul_f32_e32 v216, v211, v211
	v_mul_f32_e32 v166, v208, v208
	v_mul_f32_e32 v170, v209, v209
	v_pk_add_f32 v[168:169], v[168:169], v[216:217]
	v_pk_add_f32 v[166:167], v[166:167], v[170:171]
	s_or_b64 s[8:9], vcc, s[8:9]
	v_pk_add_f32 v[166:167], v[168:169], v[166:167]
	v_pk_add_f32 v[138:139], v[138:139], 1.0 op_sel_hi:[1,0]
	v_add_f32_e32 v129, v166, v167
	ds_bpermute_b32 v149, v195, v129
	v_pk_add_f32 v[136:137], v[136:137], 1.0 op_sel_hi:[1,0]
	v_pk_add_f32 v[134:135], v[134:135], 1.0 op_sel_hi:[1,0]
	v_pk_add_f32 v[132:133], v[132:133], 1.0 op_sel_hi:[1,0]
	v_pk_add_f32 v[130:131], v[130:131], 1.0 op_sel_hi:[1,0]
	s_waitcnt lgkmcnt(0)
; __device__ __forceinline__ unsigned cvt_pk_bf16(float lo, float hi) { f32x2v v = {lo, hi}; bf16x2_t r = __builtin_convertvector(v, bf16x2_t); return __builtin_bit_cast(unsigned, r); }
; __device__ __forceinline__ void phase_normmod(const float* src, const float* gain, const float* ada, int shoff, int scoff, bf16_t* dst) {
;     ...
;         ss = wave_sum(ss);
;         const float rstd = rsqrtf(ss * (1.0f / D_) + 1e-6f);
; #pragma unroll
;         for (int j = 0; j < 8; ++j) { const int col = 4 * (lane + 64 * j);
;             const f32x4 y = v[j] * rstd * g[j] * (sc[j] + 1.0f) + sh[j];
;             u32x2 w; w.x = cvt_pk_bf16(y[0], y[1]); w.y = cvt_pk_bf16(y[2], y[3]);
;             *(u32x2*)(dst + (size_t)m * D_ + col) = w; }
; #pragma unroll
;         for (int j = 0; j < 8; ++j) v[j] = vn[j];
	v_add_f32_e32 v129, v129, v149
	ds_bpermute_b32 v149, v197, v129
	s_waitcnt lgkmcnt(0)
	v_add_f32_e32 v129, v129, v149
	ds_bpermute_b32 v149, v203, v129
	s_waitcnt lgkmcnt(0)
	v_add_f32_e32 v129, v129, v149
	ds_bpermute_b32 v149, v204, v129
	s_waitcnt lgkmcnt(0)
	v_add_f32_e32 v129, v129, v149
	ds_bpermute_b32 v149, v205, v129
	s_waitcnt lgkmcnt(0)
	v_add_f32_e32 v129, v129, v149
	ds_bpermute_b32 v149, v206, v129
	s_waitcnt lgkmcnt(0)
	v_add_f32_e32 v129, v129, v149
	v_fmamk_f32 v129, v129, 0x3a000000, v207
	v_mul_f32_e32 v149, 0x4b800000, v129
	v_cmp_gt_f32_e32 vcc, s10, v129
	s_nop 1
	v_cndmask_b32_e32 v129, v129, v149, vcc
	v_rsq_f32_e32 v129, v129
	s_nop 0
	v_mul_f32_e32 v149, 0x45800000, v129
	v_cndmask_b32_e32 v166, v129, v149, vcc
	v_pk_mul_f32 v[168:169], v[38:39], v[166:167] op_sel_hi:[1,0]
	v_pk_mul_f32 v[170:171], v[36:37], v[166:167] op_sel_hi:[1,0]
	v_pk_mul_f32 v[176:177], v[42:43], v[166:167] op_sel_hi:[1,0]
	v_pk_mul_f32 v[178:179], v[40:41], v[166:167] op_sel_hi:[1,0]
	v_pk_mul_f32 v[180:181], v[46:47], v[166:167] op_sel_hi:[1,0]
	v_pk_mul_f32 v[182:183], v[44:45], v[166:167] op_sel_hi:[1,0]
	v_pk_mul_f32 v[188:189], v[50:51], v[166:167] op_sel_hi:[1,0]
	v_pk_mul_f32 v[214:215], v[48:49], v[166:167] op_sel_hi:[1,0]
	v_pk_mul_f32 v[216:217], v[54:55], v[166:167] op_sel_hi:[1,0]
	v_pk_mul_f32 v[218:219], v[52:53], v[166:167] op_sel_hi:[1,0]
	v_pk_mul_f32 v[220:221], v[62:63], v[166:167] op_sel_hi:[1,0]
	v_pk_mul_f32 v[222:223], v[60:61], v[166:167] op_sel_hi:[1,0]
	v_pk_mul_f32 v[224:225], v[58:59], v[166:167] op_sel_hi:[1,0]
	v_pk_mul_f32 v[226:227], v[56:57], v[166:167] op_sel_hi:[1,0]
	v_pk_mul_f32 v[228:229], v[34:35], v[166:167] op_sel_hi:[1,0]
	v_pk_mul_f32 v[166:167], v[32:33], v[166:167] op_sel_hi:[1,0]
	s_waitcnt vmcnt(0)
	v_mov_b32_e32 v210, v124
	v_mov_b32_e32 v211, v125
	v_mov_b32_e32 v208, v126
	v_mov_b32_e32 v209, v127
	v_mov_b64_e32 v[32:33], v[124:125]
	v_mov_b32_e32 v40, v92
	v_mov_b32_e32 v41, v93
	v_mov_b32_e32 v42, v94
	v_mov_b32_e32 v43, v95
	v_pk_mul_f32 v[92:93], v[0:1], v[170:171]
	v_pk_mul_f32 v[94:95], v[2:3], v[168:169]
	v_mov_b64_e32 v[34:35], v[126:127]
	v_mov_b32_e32 v36, v100
	v_mov_b32_e32 v37, v101
	v_mov_b32_e32 v38, v102
	v_mov_b32_e32 v39, v103
	v_mov_b32_e32 v44, v108
	v_mov_b32_e32 v45, v109
	v_mov_b32_e32 v46, v110
	v_mov_b32_e32 v47, v111
	v_mov_b32_e32 v48, v104
	v_mov_b32_e32 v49, v105
	v_mov_b32_e32 v50, v106
	v_mov_b32_e32 v51, v107
	v_mov_b32_e32 v52, v116
	v_mov_b32_e32 v53, v117
	v_mov_b32_e32 v54, v118
	v_mov_b32_e32 v55, v119
	v_mov_b32_e32 v60, v112
	v_mov_b32_e32 v61, v113
	v_mov_b32_e32 v62, v114
	v_mov_b32_e32 v63, v115
	v_mov_b32_e32 v56, v120
	v_mov_b32_e32 v57, v121
	v_mov_b32_e32 v58, v122
	v_mov_b32_e32 v59, v123
	v_pk_mul_f32 v[100:101], v[4:5], v[178:179]
	v_pk_mul_f32 v[102:103], v[6:7], v[176:177]
	v_pk_mul_f32 v[104:105], v[8:9], v[182:183]
	v_pk_mul_f32 v[106:107], v[10:11], v[180:181]
	v_pk_mul_f32 v[108:109], v[12:13], v[214:215]
	v_pk_mul_f32 v[110:111], v[14:15], v[188:189]
	v_pk_mul_f32 v[112:113], v[16:17], v[218:219]
	v_pk_mul_f32 v[114:115], v[18:19], v[216:217]
	v_pk_mul_f32 v[116:117], v[20:21], v[222:223]
	v_pk_mul_f32 v[118:119], v[22:23], v[220:221]
	v_pk_mul_f32 v[120:121], v[24:25], v[226:227]
	v_pk_mul_f32 v[122:123], v[26:27], v[224:225]
	v_pk_mul_f32 v[124:125], v[28:29], v[166:167]
	v_pk_mul_f32 v[126:127], v[30:31], v[228:229]
	v_pk_fma_f32 v[66:67], v[162:163], v[94:95], v[66:67]
	v_pk_fma_f32 v[64:65], v[164:165], v[92:93], v[64:65]
	v_pk_fma_f32 v[70:71], v[172:173], v[102:103], v[70:71]
	v_pk_fma_f32 v[68:69], v[174:175], v[100:101], v[68:69]
	v_pk_fma_f32 v[74:75], v[184:185], v[106:107], v[74:75]
	v_pk_fma_f32 v[72:73], v[186:187], v[104:105], v[72:73]
	v_pk_fma_f32 v[78:79], v[190:191], v[110:111], v[78:79]
	v_pk_fma_f32 v[76:77], v[192:193], v[108:109], v[76:77]
	v_pk_fma_f32 v[82:83], v[198:199], v[114:115], v[82:83]
	v_pk_fma_f32 v[80:81], v[200:201], v[112:113], v[80:81]
	v_pk_fma_f32 v[86:87], v[138:139], v[118:119], v[86:87]
	v_pk_fma_f32 v[84:85], v[136:137], v[116:117], v[84:85]
	v_pk_fma_f32 v[90:91], v[134:135], v[122:123], v[90:91]
	v_pk_fma_f32 v[88:89], v[132:133], v[120:121], v[88:89]
	v_pk_fma_f32 v[92:93], v[130:131], v[126:127], v[98:99]
	v_pk_fma_f32 v[94:95], v[212:213], v[124:125], v[96:97]
	v_cvt_pk_bf16_f32 v64, v64, v65
	v_cvt_pk_bf16_f32 v65, v66, v67
	v_cvt_pk_bf16_f32 v66, v68, v69
	v_cvt_pk_bf16_f32 v67, v70, v71
	v_cvt_pk_bf16_f32 v68, v72, v73
	v_cvt_pk_bf16_f32 v69, v74, v75
	v_cvt_pk_bf16_f32 v70, v76, v77
	v_cvt_pk_bf16_f32 v71, v78, v79
	v_cvt_pk_bf16_f32 v72, v80, v81
	v_cvt_pk_bf16_f32 v73, v82, v83
	v_cvt_pk_bf16_f32 v74, v84, v85
	v_cvt_pk_bf16_f32 v75, v86, v87
	v_cvt_pk_bf16_f32 v76, v88, v89
	v_cvt_pk_bf16_f32 v77, v90, v91
	v_cvt_pk_bf16_f32 v78, v94, v95
	v_cvt_pk_bf16_f32 v79, v92, v93
	global_store_dwordx2 v[146:147], v[64:65], off
	global_store_dwordx2 v[146:147], v[66:67], off offset:512
	global_store_dwordx2 v[146:147], v[68:69], off offset:1024
	global_store_dwordx2 v[146:147], v[70:71], off offset:1536
	global_store_dwordx2 v[146:147], v[72:73], off offset:2048
	global_store_dwordx2 v[146:147], v[74:75], off offset:2560
	global_store_dwordx2 v[146:147], v[76:77], off offset:3072
	global_store_dwordx2 v[146:147], v[78:79], off offset:3584
	v_lshl_add_u64 v[146:147], v[146:147], 0, s[4:5]
	s_andn2_b64 exec, exec, s[8:9]
	s_cbranch_execnz .LBB0_335
